# FoX pair loop: running max raised only when a row maximum exceeds it by 2^20 (rescale of O and l skipped otherwise), packed f32 softmax ops, permlane32 cross-half reductions
# speedup vs baseline: 1.0045x; 1.0035x over previous
.Lfox_outer:
	s_lshr_b32 s23, s22, 6
	s_and_b32 s24, s22, 63
	s_sub_i32 s17, 0x43, s24
	s_bitcmp1_b32 s22, 2
	s_cselect_b32 s24, s17, s24
	s_lshl_b32 s15, s24, 1
	s_lshr_b32 s25, s23, 2
	s_and_b32 s26, s23, 3
	s_lshl_b32 s17, s23, 19
	s_add_u32 s4, s20, s17
	s_addc_u32 s5, s21, 0
	s_add_u32 s6, s4, 0x1c600000
	s_addc_u32 s7, s5, 0
	s_add_u32 s4, s4, 0x1b600000
	s_addc_u32 s5, s5, 0
	s_lshl_b32 s17, s23, 16
	s_add_u32 s8, s20, s17
	s_addc_u32 s9, s21, 0
	s_add_u32 s8, s8, 0x2880000
	s_addc_u32 s9, s9, 0
	s_lshl_b32 s17, s23, 14
	s_add_u32 s10, s20, s17
	s_addc_u32 s11, s21, 0
	s_add_u32 s10, s10, 0x1da00000
	s_addc_u32 s11, s11, 0
	s_lshl_b32 s17, s25, 23
	s_lshl_b32 s18, s26, 7
	s_add_i32 s17, s17, s18
	s_add_u32 s12, s20, s17
	s_addc_u32 s13, s21, 0
	s_add_u32 s12, s12, 0x14600000
	s_addc_u32 s13, s13, 0
	s_add_u32 s2, s20, 0x5600000
	s_addc_u32 s3, s21, 0
	s_lshl_b32 s27, s25, 12
	v_lshl_add_u32 v183, s15, 5, v195
	v_lshlrev_b32_e32 v205, 11, v183
	v_lshl_add_u32 v205, v196, 3, v205
	v_add_u32_e32 v206, 0x10000, v205
	v_lshlrev_b32_e32 v184, 2, v183
	global_load_dword v199, v184, s[10:11]
	global_load_dword v203, v184, s[10:11] offset:128
	v_add_u32_e32 v183, s27, v183
	v_mul_u32_u24_e32 v183, 0x1600, v183
	v_lshl_add_u32 v183, v196, 4, v183
	s_lshl_b32 s17, s26, 7
	v_add_u32_e32 v183, s17, v183
	v_add_u32_e32 v184, 0x2c000, v183
	global_load_dwordx4 v[38:41], v183, s[2:3]
	global_load_dwordx4 v[42:45], v183, s[2:3] offset:32
	global_load_dwordx4 v[46:49], v183, s[2:3] offset:64
	global_load_dwordx4 v[50:53], v183, s[2:3] offset:96
	global_load_dwordx4 v[54:57], v184, s[2:3]
	global_load_dwordx4 v[58:61], v184, s[2:3] offset:32
	global_load_dwordx4 v[62:65], v184, s[2:3] offset:64
	global_load_dwordx4 v[66:69], v184, s[2:3] offset:96
	s_mov_b32 s16, 0
	s_lshl_b32 s17, s16, 12
	v_add_u32_e32 v207, s17, v194
	global_load_dwordx4 v[2:5], v207, s[4:5]
	global_load_dwordx4 v[6:9], v207, s[4:5] offset:1024
	global_load_dwordx4 v[10:13], v207, s[4:5] offset:2048
	global_load_dwordx4 v[14:17], v207, s[4:5] offset:3072
	s_lshl_b32 s17, s16, 9
	v_add_u32_e32 v209, s17, v190
	s_mov_b64 exec, s[44:45]
	global_load_dwordx4 v[18:21], v209, s[8:9]
	s_mov_b64 exec, -1
	s_lshl_b32 s17, s16, 12
	v_add_u32_e32 v208, s17, v194
	global_load_dwordx4 v[22:25], v208, s[6:7]
	global_load_dwordx4 v[26:29], v208, s[6:7] offset:1024
	global_load_dwordx4 v[30:33], v208, s[6:7] offset:2048
	global_load_dwordx4 v[34:37], v208, s[6:7] offset:3072
	v_mov_b32_e32 v189, 0xf149f2ca
	v_mov_b32_e32 v197, 0xf149f2ca
	v_mov_b32_e32 v198, 0
	v_mov_b32_e32 v74, 0
	v_mov_b32_e32 v75, 0
	v_mov_b32_e32 v76, 0
	v_mov_b32_e32 v77, 0
	v_mov_b32_e32 v78, 0
	v_mov_b32_e32 v79, 0
	v_mov_b32_e32 v80, 0
	v_mov_b32_e32 v81, 0
	v_mov_b32_e32 v82, 0
	v_mov_b32_e32 v83, 0
	v_mov_b32_e32 v84, 0
	v_mov_b32_e32 v85, 0
	v_mov_b32_e32 v86, 0
	v_mov_b32_e32 v87, 0
	v_mov_b32_e32 v88, 0
	v_mov_b32_e32 v89, 0
	v_mov_b32_e32 v90, 0
	v_mov_b32_e32 v91, 0
	v_mov_b32_e32 v92, 0
	v_mov_b32_e32 v93, 0
	v_mov_b32_e32 v94, 0
	v_mov_b32_e32 v95, 0
	v_mov_b32_e32 v96, 0
	v_mov_b32_e32 v97, 0
	v_mov_b32_e32 v98, 0
	v_mov_b32_e32 v99, 0
	v_mov_b32_e32 v100, 0
	v_mov_b32_e32 v101, 0
	v_mov_b32_e32 v102, 0
	v_mov_b32_e32 v103, 0
	v_mov_b32_e32 v104, 0
	v_mov_b32_e32 v105, 0
	v_mov_b32_e32 v191, 0xf149f2ca
	v_mov_b32_e32 v201, 0xf149f2ca
	v_mov_b32_e32 v202, 0
	v_mov_b32_e32 v106, 0
	v_mov_b32_e32 v107, 0
	v_mov_b32_e32 v108, 0
	v_mov_b32_e32 v109, 0
	v_mov_b32_e32 v110, 0
	v_mov_b32_e32 v111, 0
	v_mov_b32_e32 v112, 0
	v_mov_b32_e32 v113, 0
	v_mov_b32_e32 v114, 0
	v_mov_b32_e32 v115, 0
	v_mov_b32_e32 v116, 0
	v_mov_b32_e32 v117, 0
	v_mov_b32_e32 v118, 0
	v_mov_b32_e32 v119, 0
	v_mov_b32_e32 v120, 0
	v_mov_b32_e32 v121, 0
	v_mov_b32_e32 v122, 0
	v_mov_b32_e32 v123, 0
	v_mov_b32_e32 v124, 0
	v_mov_b32_e32 v125, 0
	v_mov_b32_e32 v126, 0
	v_mov_b32_e32 v127, 0
	v_mov_b32_e32 v128, 0
	v_mov_b32_e32 v129, 0
	v_mov_b32_e32 v130, 0
	v_mov_b32_e32 v131, 0
	v_mov_b32_e32 v132, 0
	v_mov_b32_e32 v133, 0
	v_mov_b32_e32 v134, 0
	v_mov_b32_e32 v135, 0
	v_mov_b32_e32 v136, 0
	v_mov_b32_e32 v137, 0
	s_waitcnt vmcnt(9)
	v_mul_f32_e32 v199, 0x3fb8aa3b, v199
	v_mul_f32_e32 v203, 0x3fb8aa3b, v203
	s_cmp_eq_u32 s15, 0
	s_cbranch_scc1 .Lfox_tail
.Lfox_loop:
	s_waitcnt vmcnt(4)
	v_mfma_f32_32x32x16_bf16 v[138:153], v[2:5], v[38:41], 0
	v_mfma_f32_32x32x16_bf16 v[138:153], v[6:9], v[42:45], v[138:153]
	v_mfma_f32_32x32x16_bf16 v[138:153], v[10:13], v[46:49], v[138:153]
	v_mfma_f32_32x32x16_bf16 v[138:153], v[14:17], v[50:53], v[138:153]
	v_mfma_f32_32x32x16_bf16 v[138:153], v[18:21], v[70:73], v[138:153]
	v_mfma_f32_32x32x16_bf16 v[154:169], v[2:5], v[54:57], 0
	s_nop 7
	s_nop 4
	v_max3_f32 v183, v138, v139, v140
	v_max3_f32 v184, v141, v142, v143
	v_max3_f32 v185, v144, v145, v146
	v_max3_f32 v186, v147, v148, v149
	v_max3_f32 v187, v150, v151, v152
	v_max3_f32 v183, v183, v184, v185
	v_max3_f32 v186, v186, v187, v153
	v_max_f32_e32 v183, v183, v186
	v_mov_b32_e32 v184, v183
	v_mfma_f32_32x32x16_bf16 v[154:169], v[6:9], v[58:61], v[154:169]
	s_nop 1
	v_permlane32_swap_b32_e32 v184, v183
	v_max_f32_e32 v183, v183, v184
	v_fma_f32 v183, v183, s14, v199
	v_cmp_lt_f32_e32 vcc, v189, v183
	s_cbranch_vccz .Lfox_keep1
	v_max_f32_e32 v184, v197, v183
	v_sub_f32_e32 v186, v197, v184
	v_exp_f32_e32 v186, v186
	v_mov_b32_e32 v197, v184
	v_sub_f32_e32 v200, v199, v184
	v_add_f32_e32 v189, 0x41a00000, v184
	v_mul_f32_e32 v198, v198, v186
	v_pk_mul_f32 v[74:75], v[74:75], v[186:187] op_sel_hi:[1,0]
	v_pk_mul_f32 v[76:77], v[76:77], v[186:187] op_sel_hi:[1,0]
	v_pk_mul_f32 v[78:79], v[78:79], v[186:187] op_sel_hi:[1,0]
	v_pk_mul_f32 v[80:81], v[80:81], v[186:187] op_sel_hi:[1,0]
	v_pk_mul_f32 v[82:83], v[82:83], v[186:187] op_sel_hi:[1,0]
	v_pk_mul_f32 v[84:85], v[84:85], v[186:187] op_sel_hi:[1,0]
	v_pk_mul_f32 v[86:87], v[86:87], v[186:187] op_sel_hi:[1,0]
	v_pk_mul_f32 v[88:89], v[88:89], v[186:187] op_sel_hi:[1,0]
	v_pk_mul_f32 v[90:91], v[90:91], v[186:187] op_sel_hi:[1,0]
	v_pk_mul_f32 v[92:93], v[92:93], v[186:187] op_sel_hi:[1,0]
	v_pk_mul_f32 v[94:95], v[94:95], v[186:187] op_sel_hi:[1,0]
	v_pk_mul_f32 v[96:97], v[96:97], v[186:187] op_sel_hi:[1,0]
	v_pk_mul_f32 v[98:99], v[98:99], v[186:187] op_sel_hi:[1,0]
	v_pk_mul_f32 v[100:101], v[100:101], v[186:187] op_sel_hi:[1,0]
	v_pk_mul_f32 v[102:103], v[102:103], v[186:187] op_sel_hi:[1,0]
	v_pk_mul_f32 v[104:105], v[104:105], v[186:187] op_sel_hi:[1,0]
.Lfox_keep1:
	v_pk_fma_f32 v[138:139], v[138:139], v[192:193], v[200:201] op_sel_hi:[1,0,0]
	v_exp_f32_e32 v138, v138
	v_exp_f32_e32 v139, v139
	v_mfma_f32_32x32x16_bf16 v[154:169], v[10:13], v[62:65], v[154:169]
	v_pk_fma_f32 v[140:141], v[140:141], v[192:193], v[200:201] op_sel_hi:[1,0,0]
	v_exp_f32_e32 v140, v140
	v_exp_f32_e32 v141, v141
	v_pk_fma_f32 v[142:143], v[142:143], v[192:193], v[200:201] op_sel_hi:[1,0,0]
	v_exp_f32_e32 v142, v142
	v_exp_f32_e32 v143, v143
	v_pk_fma_f32 v[144:145], v[144:145], v[192:193], v[200:201] op_sel_hi:[1,0,0]
	v_exp_f32_e32 v144, v144
	v_exp_f32_e32 v145, v145
	v_mfma_f32_32x32x16_bf16 v[154:169], v[14:17], v[66:69], v[154:169]
	v_pk_fma_f32 v[146:147], v[146:147], v[192:193], v[200:201] op_sel_hi:[1,0,0]
	v_exp_f32_e32 v146, v146
	v_exp_f32_e32 v147, v147
	v_pk_fma_f32 v[148:149], v[148:149], v[192:193], v[200:201] op_sel_hi:[1,0,0]
	v_exp_f32_e32 v148, v148
	v_exp_f32_e32 v149, v149
	v_pk_fma_f32 v[150:151], v[150:151], v[192:193], v[200:201] op_sel_hi:[1,0,0]
	v_exp_f32_e32 v150, v150
	v_exp_f32_e32 v151, v151
	v_mfma_f32_32x32x16_bf16 v[154:169], v[18:21], v[70:73], v[154:169]
	s_add_i32 s18, s16, 1
	s_lshl_b32 s17, s18, 12
	v_add_u32_e32 v207, s17, v194
	global_load_dwordx4 v[2:5], v207, s[4:5]
	global_load_dwordx4 v[6:9], v207, s[4:5] offset:1024
	global_load_dwordx4 v[10:13], v207, s[4:5] offset:2048
	global_load_dwordx4 v[14:17], v207, s[4:5] offset:3072
	s_lshl_b32 s17, s18, 9
	v_add_u32_e32 v209, s17, v190
	s_mov_b64 exec, s[44:45]
	global_load_dwordx4 v[18:21], v209, s[8:9]
	s_mov_b64 exec, -1
	v_pk_fma_f32 v[152:153], v[152:153], v[192:193], v[200:201] op_sel_hi:[1,0,0]
	v_exp_f32_e32 v152, v152
	v_exp_f32_e32 v153, v153
	v_pk_add_f32 v[184:185], v[138:139], v[140:141]
	v_pk_add_f32 v[186:187], v[142:143], v[144:145]
	v_pk_add_f32 v[184:185], v[184:185], v[146:147]
	v_pk_add_f32 v[186:187], v[186:187], v[148:149]
	v_pk_add_f32 v[184:185], v[184:185], v[150:151]
	v_pk_add_f32 v[186:187], v[186:187], v[152:153]
	v_pk_add_f32 v[184:185], v[184:185], v[186:187]
	v_add_f32_e32 v183, v184, v185
	v_add_f32_e32 v198, v198, v183
	v_cvt_pk_bf16_f32 v138, v138, v139
	v_cvt_pk_bf16_f32 v139, v140, v141
	v_cvt_pk_bf16_f32 v140, v142, v143
	v_cvt_pk_bf16_f32 v141, v144, v145
	v_cvt_pk_bf16_f32 v142, v146, v147
	v_cvt_pk_bf16_f32 v143, v148, v149
	v_cvt_pk_bf16_f32 v144, v150, v151
	v_cvt_pk_bf16_f32 v145, v152, v153
	v_max3_f32 v183, v154, v155, v156
	v_max3_f32 v184, v157, v158, v159
	v_max3_f32 v185, v160, v161, v162
	s_waitcnt vmcnt(5)
	v_mfma_f32_32x32x16_bf16 v[74:89], v[22:25], v[138:141], v[74:89]
	v_max3_f32 v186, v163, v164, v165
	v_max3_f32 v187, v166, v167, v168
	v_max3_f32 v183, v183, v184, v185
	v_mfma_f32_32x32x16_bf16 v[90:105], v[30:33], v[138:141], v[90:105]
	v_max3_f32 v186, v186, v187, v169
	v_max_f32_e32 v183, v183, v186
	v_mov_b32_e32 v184, v183
	s_nop 1
	v_permlane32_swap_b32_e32 v184, v183
	v_max_f32_e32 v183, v183, v184
	v_fma_f32 v183, v183, s14, v203
	v_cmp_lt_f32_e32 vcc, v191, v183
	s_cbranch_vccz .Lfox_keep2
	v_max_f32_e32 v184, v201, v183
	v_sub_f32_e32 v186, v201, v184
	v_exp_f32_e32 v186, v186
	v_mov_b32_e32 v201, v184
	v_sub_f32_e32 v204, v203, v184
	v_add_f32_e32 v191, 0x41a00000, v184
	v_mul_f32_e32 v202, v202, v186
	v_pk_mul_f32 v[106:107], v[106:107], v[186:187] op_sel_hi:[1,0]
	v_pk_mul_f32 v[108:109], v[108:109], v[186:187] op_sel_hi:[1,0]
	v_pk_mul_f32 v[110:111], v[110:111], v[186:187] op_sel_hi:[1,0]
	v_pk_mul_f32 v[112:113], v[112:113], v[186:187] op_sel_hi:[1,0]
	v_pk_mul_f32 v[114:115], v[114:115], v[186:187] op_sel_hi:[1,0]
	v_pk_mul_f32 v[116:117], v[116:117], v[186:187] op_sel_hi:[1,0]
	v_pk_mul_f32 v[118:119], v[118:119], v[186:187] op_sel_hi:[1,0]
	v_pk_mul_f32 v[120:121], v[120:121], v[186:187] op_sel_hi:[1,0]
	v_pk_mul_f32 v[122:123], v[122:123], v[186:187] op_sel_hi:[1,0]
	v_pk_mul_f32 v[124:125], v[124:125], v[186:187] op_sel_hi:[1,0]
	v_pk_mul_f32 v[126:127], v[126:127], v[186:187] op_sel_hi:[1,0]
	v_pk_mul_f32 v[128:129], v[128:129], v[186:187] op_sel_hi:[1,0]
	v_pk_mul_f32 v[130:131], v[130:131], v[186:187] op_sel_hi:[1,0]
	v_pk_mul_f32 v[132:133], v[132:133], v[186:187] op_sel_hi:[1,0]
	v_pk_mul_f32 v[134:135], v[134:135], v[186:187] op_sel_hi:[1,0]
	v_pk_mul_f32 v[136:137], v[136:137], v[186:187] op_sel_hi:[1,0]
.Lfox_keep2:
	v_pk_fma_f32 v[154:155], v[154:155], v[192:193], v[204:205] op_sel_hi:[1,0,0]
	v_exp_f32_e32 v154, v154
	v_exp_f32_e32 v155, v155
	v_pk_fma_f32 v[156:157], v[156:157], v[192:193], v[204:205] op_sel_hi:[1,0,0]
	v_mfma_f32_32x32x16_bf16 v[74:89], v[26:29], v[142:145], v[74:89]
	v_exp_f32_e32 v156, v156
	v_exp_f32_e32 v157, v157
	v_pk_fma_f32 v[158:159], v[158:159], v[192:193], v[204:205] op_sel_hi:[1,0,0]
	v_exp_f32_e32 v158, v158
	v_mfma_f32_32x32x16_bf16 v[90:105], v[34:37], v[142:145], v[90:105]
	v_exp_f32_e32 v159, v159
	v_pk_fma_f32 v[160:161], v[160:161], v[192:193], v[204:205] op_sel_hi:[1,0,0]
	v_exp_f32_e32 v160, v160
	v_exp_f32_e32 v161, v161
	v_pk_fma_f32 v[162:163], v[162:163], v[192:193], v[204:205] op_sel_hi:[1,0,0]
	v_exp_f32_e32 v162, v162
	v_exp_f32_e32 v163, v163
	v_pk_fma_f32 v[164:165], v[164:165], v[192:193], v[204:205] op_sel_hi:[1,0,0]
	v_exp_f32_e32 v164, v164
	v_exp_f32_e32 v165, v165
	v_pk_fma_f32 v[166:167], v[166:167], v[192:193], v[204:205] op_sel_hi:[1,0,0]
	v_exp_f32_e32 v166, v166
	v_exp_f32_e32 v167, v167
	v_pk_fma_f32 v[168:169], v[168:169], v[192:193], v[204:205] op_sel_hi:[1,0,0]
	v_exp_f32_e32 v168, v168
	v_exp_f32_e32 v169, v169
	v_pk_add_f32 v[184:185], v[154:155], v[156:157]
	v_pk_add_f32 v[186:187], v[158:159], v[160:161]
	v_pk_add_f32 v[184:185], v[184:185], v[162:163]
	v_pk_add_f32 v[186:187], v[186:187], v[164:165]
	v_pk_add_f32 v[184:185], v[184:185], v[166:167]
	v_pk_add_f32 v[186:187], v[186:187], v[168:169]
	v_pk_add_f32 v[184:185], v[184:185], v[186:187]
	v_add_f32_e32 v183, v184, v185
	v_add_f32_e32 v202, v202, v183
	v_cvt_pk_bf16_f32 v154, v154, v155
	v_cvt_pk_bf16_f32 v155, v156, v157
	v_cvt_pk_bf16_f32 v156, v158, v159
	v_cvt_pk_bf16_f32 v157, v160, v161
	v_cvt_pk_bf16_f32 v158, v162, v163
	v_cvt_pk_bf16_f32 v159, v164, v165
	v_cvt_pk_bf16_f32 v160, v166, v167
	v_cvt_pk_bf16_f32 v161, v168, v169
	s_nop 1
	v_mfma_f32_32x32x16_bf16 v[106:121], v[22:25], v[154:157], v[106:121]
	v_mfma_f32_32x32x16_bf16 v[122:137], v[30:33], v[154:157], v[122:137]
	v_mfma_f32_32x32x16_bf16 v[106:121], v[26:29], v[158:161], v[106:121]
	v_mfma_f32_32x32x16_bf16 v[122:137], v[34:37], v[158:161], v[122:137]
	s_lshl_b32 s17, s18, 12
	v_add_u32_e32 v208, s17, v194
	global_load_dwordx4 v[22:25], v208, s[6:7]
	global_load_dwordx4 v[26:29], v208, s[6:7] offset:1024
	global_load_dwordx4 v[30:33], v208, s[6:7] offset:2048
	global_load_dwordx4 v[34:37], v208, s[6:7] offset:3072
	s_add_i32 s16, s16, 1
	s_cmp_lt_u32 s16, s15
	s_cbranch_scc1 .Lfox_loop
.Lfox_tail:
	s_waitcnt vmcnt(4)
	v_mfma_f32_32x32x16_bf16 v[138:153], v[2:5], v[38:41], 0
	v_mfma_f32_32x32x16_bf16 v[138:153], v[6:9], v[42:45], v[138:153]
	v_mfma_f32_32x32x16_bf16 v[138:153], v[10:13], v[46:49], v[138:153]
	v_mfma_f32_32x32x16_bf16 v[138:153], v[14:17], v[50:53], v[138:153]
	v_mfma_f32_32x32x16_bf16 v[138:153], v[18:21], v[70:73], v[138:153]
	v_mfma_f32_32x32x16_bf16 v[154:169], v[2:5], v[54:57], 0
	s_nop 7
	s_nop 4
	v_cmp_le_i32_e64 s[34:35], 0, v170
	v_cmp_le_i32_e64 s[36:37], 1, v170
	v_cmp_le_i32_e64 s[38:39], 2, v170
	v_cmp_le_i32_e64 s[40:41], 3, v170
	v_cmp_le_i32_e32 vcc, 8, v170
	v_cndmask_b32_e64 v138, v193, v138, s[34:35]
	v_cndmask_b32_e64 v139, v193, v139, s[36:37]
	v_cndmask_b32_e64 v140, v193, v140, s[38:39]
	v_cndmask_b32_e64 v141, v193, v141, s[40:41]
	v_cndmask_b32_e64 v142, v193, v142, vcc
	v_cmp_le_i32_e64 s[34:35], 9, v170
	v_cmp_le_i32_e64 s[36:37], 10, v170
	v_cmp_le_i32_e64 s[38:39], 11, v170
	v_cmp_le_i32_e64 s[40:41], 16, v170
	v_cmp_le_i32_e32 vcc, 17, v170
	v_cndmask_b32_e64 v143, v193, v143, s[34:35]
	v_cndmask_b32_e64 v144, v193, v144, s[36:37]
	v_cndmask_b32_e64 v145, v193, v145, s[38:39]
	v_cndmask_b32_e64 v146, v193, v146, s[40:41]
	v_cndmask_b32_e64 v147, v193, v147, vcc
	v_cmp_le_i32_e64 s[34:35], 18, v170
	v_cmp_le_i32_e64 s[36:37], 19, v170
	v_cmp_le_i32_e64 s[38:39], 24, v170
	v_cmp_le_i32_e64 s[40:41], 25, v170
	v_cmp_le_i32_e32 vcc, 26, v170
	v_cndmask_b32_e64 v148, v193, v148, s[34:35]
	v_cndmask_b32_e64 v149, v193, v149, s[36:37]
	v_cndmask_b32_e64 v150, v193, v150, s[38:39]
	v_cndmask_b32_e64 v151, v193, v151, s[40:41]
	v_cndmask_b32_e64 v152, v193, v152, vcc
	v_cmp_le_i32_e64 s[34:35], 27, v170
	s_nop 1
	v_cndmask_b32_e64 v153, v193, v153, s[34:35]
	v_max3_f32 v183, v138, v139, v140
	v_max3_f32 v184, v141, v142, v143
	v_max3_f32 v185, v144, v145, v146
	v_max3_f32 v186, v147, v148, v149
	v_max3_f32 v187, v150, v151, v152
	v_max3_f32 v183, v183, v184, v185
	v_max3_f32 v186, v186, v187, v153
	v_max_f32_e32 v183, v183, v186
	v_mov_b32_e32 v184, v183
	v_mfma_f32_32x32x16_bf16 v[154:169], v[6:9], v[58:61], v[154:169]
	s_nop 1
	v_permlane32_swap_b32_e32 v184, v183
	v_max_f32_e32 v183, v183, v184
	v_fma_f32 v183, v183, s14, v199
	v_cmp_lt_f32_e32 vcc, v189, v183
	s_cbranch_vccz .Lfox_keep3
	v_max_f32_e32 v184, v197, v183
	v_sub_f32_e32 v186, v197, v184
	v_exp_f32_e32 v186, v186
	v_mov_b32_e32 v197, v184
	v_sub_f32_e32 v200, v199, v184
	v_add_f32_e32 v189, 0x41a00000, v184
	v_mul_f32_e32 v198, v198, v186
	v_pk_mul_f32 v[74:75], v[74:75], v[186:187] op_sel_hi:[1,0]
	v_pk_mul_f32 v[76:77], v[76:77], v[186:187] op_sel_hi:[1,0]
	v_pk_mul_f32 v[78:79], v[78:79], v[186:187] op_sel_hi:[1,0]
	v_pk_mul_f32 v[80:81], v[80:81], v[186:187] op_sel_hi:[1,0]
	v_pk_mul_f32 v[82:83], v[82:83], v[186:187] op_sel_hi:[1,0]
	v_pk_mul_f32 v[84:85], v[84:85], v[186:187] op_sel_hi:[1,0]
	v_pk_mul_f32 v[86:87], v[86:87], v[186:187] op_sel_hi:[1,0]
	v_pk_mul_f32 v[88:89], v[88:89], v[186:187] op_sel_hi:[1,0]
	v_pk_mul_f32 v[90:91], v[90:91], v[186:187] op_sel_hi:[1,0]
	v_pk_mul_f32 v[92:93], v[92:93], v[186:187] op_sel_hi:[1,0]
	v_pk_mul_f32 v[94:95], v[94:95], v[186:187] op_sel_hi:[1,0]
	v_pk_mul_f32 v[96:97], v[96:97], v[186:187] op_sel_hi:[1,0]
	v_pk_mul_f32 v[98:99], v[98:99], v[186:187] op_sel_hi:[1,0]
	v_pk_mul_f32 v[100:101], v[100:101], v[186:187] op_sel_hi:[1,0]
	v_pk_mul_f32 v[102:103], v[102:103], v[186:187] op_sel_hi:[1,0]
	v_pk_mul_f32 v[104:105], v[104:105], v[186:187] op_sel_hi:[1,0]

.Lfox_keep4:
	v_pk_fma_f32 v[154:155], v[154:155], v[192:193], v[204:205] op_sel_hi:[1,0,0]
	v_exp_f32_e32 v154, v154
	v_exp_f32_e32 v155, v155
	v_pk_fma_f32 v[156:157], v[156:157], v[192:193], v[204:205] op_sel_hi:[1,0,0]
	v_mfma_f32_32x32x16_bf16 v[74:89], v[26:29], v[142:145], v[74:89]
	v_exp_f32_e32 v156, v156
	v_exp_f32_e32 v157, v157
	v_pk_fma_f32 v[158:159], v[158:159], v[192:193], v[204:205] op_sel_hi:[1,0,0]
	v_exp_f32_e32 v158, v158
	v_mfma_f32_32x32x16_bf16 v[90:105], v[34:37], v[142:145], v[90:105]
	v_exp_f32_e32 v159, v159
	v_pk_fma_f32 v[160:161], v[160:161], v[192:193], v[204:205] op_sel_hi:[1,0,0]
	v_exp_f32_e32 v160, v160
	v_exp_f32_e32 v161, v161
	v_pk_fma_f32 v[162:163], v[162:163], v[192:193], v[204:205] op_sel_hi:[1,0,0]
	v_exp_f32_e32 v162, v162
	v_exp_f32_e32 v163, v163
	v_pk_fma_f32 v[164:165], v[164:165], v[192:193], v[204:205] op_sel_hi:[1,0,0]
	v_exp_f32_e32 v164, v164
	v_exp_f32_e32 v165, v165
	v_pk_fma_f32 v[166:167], v[166:167], v[192:193], v[204:205] op_sel_hi:[1,0,0]
	v_exp_f32_e32 v166, v166
	v_exp_f32_e32 v167, v167
	v_pk_fma_f32 v[168:169], v[168:169], v[192:193], v[204:205] op_sel_hi:[1,0,0]
	v_exp_f32_e32 v168, v168
	v_exp_f32_e32 v169, v169
	v_pk_add_f32 v[184:185], v[154:155], v[156:157]
	v_pk_add_f32 v[186:187], v[158:159], v[160:161]
	v_pk_add_f32 v[184:185], v[184:185], v[162:163]
	v_pk_add_f32 v[186:187], v[186:187], v[164:165]
	v_pk_add_f32 v[184:185], v[184:185], v[166:167]
	v_pk_add_f32 v[186:187], v[186:187], v[168:169]
	v_pk_add_f32 v[184:185], v[184:185], v[186:187]
	v_add_f32_e32 v183, v184, v185
	v_add_f32_e32 v202, v202, v183
	v_cvt_pk_bf16_f32 v154, v154, v155
	v_cvt_pk_bf16_f32 v155, v156, v157
	v_cvt_pk_bf16_f32 v156, v158, v159
	v_cvt_pk_bf16_f32 v157, v160, v161
	v_cvt_pk_bf16_f32 v158, v162, v163
	v_cvt_pk_bf16_f32 v159, v164, v165
	v_cvt_pk_bf16_f32 v160, v166, v167
	v_cvt_pk_bf16_f32 v161, v168, v169
	s_nop 1
	v_mfma_f32_32x32x16_bf16 v[106:121], v[22:25], v[154:157], v[106:121]
	v_mfma_f32_32x32x16_bf16 v[122:137], v[30:33], v[154:157], v[122:137]
	v_mfma_f32_32x32x16_bf16 v[106:121], v[26:29], v[158:161], v[106:121]
	v_mfma_f32_32x32x16_bf16 v[122:137], v[34:37], v[158:161], v[122:137]
	s_lshl_b32 s17, s18, 12
	v_add_u32_e32 v208, s17, v194
	global_load_dwordx4 v[22:25], v208, s[6:7]
	global_load_dwordx4 v[26:29], v208, s[6:7] offset:1024
	global_load_dwordx4 v[30:33], v208, s[6:7] offset:2048
	global_load_dwordx4 v[34:37], v208, s[6:7] offset:3072
	s_add_i32 s16, s16, 1
	s_waitcnt vmcnt(4)
	v_mfma_f32_32x32x16_bf16 v[154:169], v[2:5], v[54:57], 0
	v_mfma_f32_32x32x16_bf16 v[154:169], v[6:9], v[58:61], v[154:169]
	v_mfma_f32_32x32x16_bf16 v[154:169], v[10:13], v[62:65], v[154:169]
	v_mfma_f32_32x32x16_bf16 v[154:169], v[14:17], v[66:69], v[154:169]
	v_mfma_f32_32x32x16_bf16 v[154:169], v[18:21], v[70:73], v[154:169]
	s_nop 7
	s_nop 4
	v_cmp_le_i32_e64 s[34:35], 0, v170
	v_cmp_le_i32_e64 s[36:37], 1, v170
	v_cmp_le_i32_e64 s[38:39], 2, v170
	v_cmp_le_i32_e64 s[40:41], 3, v170
	v_cmp_le_i32_e32 vcc, 8, v170
	v_cndmask_b32_e64 v154, v193, v154, s[34:35]
	v_cndmask_b32_e64 v155, v193, v155, s[36:37]
	v_cndmask_b32_e64 v156, v193, v156, s[38:39]
	v_cndmask_b32_e64 v157, v193, v157, s[40:41]
	v_cndmask_b32_e64 v158, v193, v158, vcc
	v_cmp_le_i32_e64 s[34:35], 9, v170
	v_cmp_le_i32_e64 s[36:37], 10, v170
	v_cmp_le_i32_e64 s[38:39], 11, v170
	v_cmp_le_i32_e64 s[40:41], 16, v170
	v_cmp_le_i32_e32 vcc, 17, v170
	v_cndmask_b32_e64 v159, v193, v159, s[34:35]
	v_cndmask_b32_e64 v160, v193, v160, s[36:37]
	v_cndmask_b32_e64 v161, v193, v161, s[38:39]
	v_cndmask_b32_e64 v162, v193, v162, s[40:41]
	v_cndmask_b32_e64 v163, v193, v163, vcc
	v_cmp_le_i32_e64 s[34:35], 18, v170
	v_cmp_le_i32_e64 s[36:37], 19, v170
	v_cmp_le_i32_e64 s[38:39], 24, v170
	v_cmp_le_i32_e64 s[40:41], 25, v170
	v_cmp_le_i32_e32 vcc, 26, v170
	v_cndmask_b32_e64 v164, v193, v164, s[34:35]
	v_cndmask_b32_e64 v165, v193, v165, s[36:37]
	v_cndmask_b32_e64 v166, v193, v166, s[38:39]
	v_cndmask_b32_e64 v167, v193, v167, s[40:41]
	v_cndmask_b32_e64 v168, v193, v168, vcc
	v_cmp_le_i32_e64 s[34:35], 27, v170
	s_nop 1
	v_cndmask_b32_e64 v169, v193, v169, s[34:35]
	v_max3_f32 v183, v154, v155, v156
	v_max3_f32 v184, v157, v158, v159
	v_max3_f32 v185, v160, v161, v162
	v_max3_f32 v186, v163, v164, v165
	v_max3_f32 v187, v166, v167, v168
	v_max3_f32 v183, v183, v184, v185
	v_max3_f32 v186, v186, v187, v169
	v_max_f32_e32 v183, v183, v186
	v_mov_b32_e32 v184, v183
	s_nop 1
	v_permlane32_swap_b32_e32 v184, v183
	v_max_f32_e32 v183, v183, v184
	v_fma_f32 v183, v183, s14, v203
	v_cmp_lt_f32_e32 vcc, v191, v183
	s_cbranch_vccz .Lfox_keep5
	v_max_f32_e32 v184, v201, v183
	v_sub_f32_e32 v186, v201, v184
	v_exp_f32_e32 v186, v186
	v_mov_b32_e32 v201, v184
	v_sub_f32_e32 v204, v203, v184
	v_add_f32_e32 v191, 0x41a00000, v184
	v_mul_f32_e32 v202, v202, v186
	v_pk_mul_f32 v[106:107], v[106:107], v[186:187] op_sel_hi:[1,0]
	v_pk_mul_f32 v[108:109], v[108:109], v[186:187] op_sel_hi:[1,0]
	v_pk_mul_f32 v[110:111], v[110:111], v[186:187] op_sel_hi:[1,0]
	v_pk_mul_f32 v[112:113], v[112:113], v[186:187] op_sel_hi:[1,0]
	v_pk_mul_f32 v[114:115], v[114:115], v[186:187] op_sel_hi:[1,0]
	v_pk_mul_f32 v[116:117], v[116:117], v[186:187] op_sel_hi:[1,0]
	v_pk_mul_f32 v[118:119], v[118:119], v[186:187] op_sel_hi:[1,0]
	v_pk_mul_f32 v[120:121], v[120:121], v[186:187] op_sel_hi:[1,0]
	v_pk_mul_f32 v[122:123], v[122:123], v[186:187] op_sel_hi:[1,0]
	v_pk_mul_f32 v[124:125], v[124:125], v[186:187] op_sel_hi:[1,0]
	v_pk_mul_f32 v[126:127], v[126:127], v[186:187] op_sel_hi:[1,0]
	v_pk_mul_f32 v[128:129], v[128:129], v[186:187] op_sel_hi:[1,0]
	v_pk_mul_f32 v[130:131], v[130:131], v[186:187] op_sel_hi:[1,0]
	v_pk_mul_f32 v[132:133], v[132:133], v[186:187] op_sel_hi:[1,0]
	v_pk_mul_f32 v[134:135], v[134:135], v[186:187] op_sel_hi:[1,0]
	v_pk_mul_f32 v[136:137], v[136:137], v[186:187] op_sel_hi:[1,0]
.Lfox_keep5:
	s_waitcnt vmcnt(0)
	v_pk_fma_f32 v[154:155], v[154:155], v[192:193], v[204:205] op_sel_hi:[1,0,0]
	v_exp_f32_e32 v154, v154
	v_exp_f32_e32 v155, v155
	v_pk_fma_f32 v[156:157], v[156:157], v[192:193], v[204:205] op_sel_hi:[1,0,0]
	v_exp_f32_e32 v156, v156
	v_exp_f32_e32 v157, v157
	v_pk_fma_f32 v[158:159], v[158:159], v[192:193], v[204:205] op_sel_hi:[1,0,0]
	v_exp_f32_e32 v158, v158
	v_exp_f32_e32 v159, v159
	v_pk_fma_f32 v[160:161], v[160:161], v[192:193], v[204:205] op_sel_hi:[1,0,0]
	v_exp_f32_e32 v160, v160
	v_exp_f32_e32 v161, v161
	v_pk_fma_f32 v[162:163], v[162:163], v[192:193], v[204:205] op_sel_hi:[1,0,0]
	v_exp_f32_e32 v162, v162
	v_exp_f32_e32 v163, v163
	v_pk_fma_f32 v[164:165], v[164:165], v[192:193], v[204:205] op_sel_hi:[1,0,0]
	v_exp_f32_e32 v164, v164
	v_exp_f32_e32 v165, v165
	v_pk_fma_f32 v[166:167], v[166:167], v[192:193], v[204:205] op_sel_hi:[1,0,0]
	v_exp_f32_e32 v166, v166
	v_exp_f32_e32 v167, v167
	v_pk_fma_f32 v[168:169], v[168:169], v[192:193], v[204:205] op_sel_hi:[1,0,0]
	v_exp_f32_e32 v168, v168
	v_exp_f32_e32 v169, v169
	v_pk_add_f32 v[184:185], v[154:155], v[156:157]
	v_pk_add_f32 v[186:187], v[158:159], v[160:161]
	v_pk_add_f32 v[184:185], v[184:185], v[162:163]
	v_pk_add_f32 v[186:187], v[186:187], v[164:165]
	v_pk_add_f32 v[184:185], v[184:185], v[166:167]
	v_pk_add_f32 v[186:187], v[186:187], v[168:169]
	v_pk_add_f32 v[184:185], v[184:185], v[186:187]
	v_add_f32_e32 v183, v184, v185
	v_add_f32_e32 v202, v202, v183
	v_cvt_pk_bf16_f32 v154, v154, v155
	v_cvt_pk_bf16_f32 v155, v156, v157
	v_cvt_pk_bf16_f32 v156, v158, v159
	v_cvt_pk_bf16_f32 v157, v160, v161
	v_cvt_pk_bf16_f32 v158, v162, v163
	v_cvt_pk_bf16_f32 v159, v164, v165
	v_cvt_pk_bf16_f32 v160, v166, v167
	v_cvt_pk_bf16_f32 v161, v168, v169
	s_nop 1
	v_mfma_f32_32x32x16_bf16 v[106:121], v[22:25], v[154:157], v[106:121]
	v_mfma_f32_32x32x16_bf16 v[122:137], v[30:33], v[154:157], v[122:137]
	v_mfma_f32_32x32x16_bf16 v[106:121], v[26:29], v[158:161], v[106:121]
	v_mfma_f32_32x32x16_bf16 v[122:137], v[34:37], v[158:161], v[122:137]
	s_nop 7
	s_nop 7
	v_mov_b32_e32 v184, v198
	s_nop 1
	v_permlane32_swap_b32_e32 v184, v198
	v_add_f32_e32 v198, v198, v184
	v_rcp_f32_e32 v186, v198
	s_nop 0
	v_fma_f32 v184, -v198, v186, 1.0
	v_fma_f32 v186, v186, v184, v186
	v_pk_mul_f32 v[74:75], v[74:75], v[186:187] op_sel_hi:[1,0]
	v_pk_mul_f32 v[76:77], v[76:77], v[186:187] op_sel_hi:[1,0]
	v_pk_mul_f32 v[78:79], v[78:79], v[186:187] op_sel_hi:[1,0]
	v_pk_mul_f32 v[80:81], v[80:81], v[186:187] op_sel_hi:[1,0]
	v_pk_mul_f32 v[82:83], v[82:83], v[186:187] op_sel_hi:[1,0]
	v_pk_mul_f32 v[84:85], v[84:85], v[186:187] op_sel_hi:[1,0]
	v_pk_mul_f32 v[86:87], v[86:87], v[186:187] op_sel_hi:[1,0]
	v_pk_mul_f32 v[88:89], v[88:89], v[186:187] op_sel_hi:[1,0]
	v_pk_mul_f32 v[90:91], v[90:91], v[186:187] op_sel_hi:[1,0]
	v_pk_mul_f32 v[92:93], v[92:93], v[186:187] op_sel_hi:[1,0]
	v_pk_mul_f32 v[94:95], v[94:95], v[186:187] op_sel_hi:[1,0]
	v_pk_mul_f32 v[96:97], v[96:97], v[186:187] op_sel_hi:[1,0]
	v_pk_mul_f32 v[98:99], v[98:99], v[186:187] op_sel_hi:[1,0]
	v_pk_mul_f32 v[100:101], v[100:101], v[186:187] op_sel_hi:[1,0]
	v_pk_mul_f32 v[102:103], v[102:103], v[186:187] op_sel_hi:[1,0]
	v_pk_mul_f32 v[104:105], v[104:105], v[186:187] op_sel_hi:[1,0]
	v_cvt_pk_bf16_f32 v74, v74, v75
	v_cvt_pk_bf16_f32 v75, v76, v77
	global_store_dwordx2 v205, v[74:75], s[12:13]
	v_cvt_pk_bf16_f32 v78, v78, v79
	v_cvt_pk_bf16_f32 v79, v80, v81
	global_store_dwordx2 v205, v[78:79], s[12:13] offset:16
	v_cvt_pk_bf16_f32 v82, v82, v83
	v_cvt_pk_bf16_f32 v83, v84, v85
	global_store_dwordx2 v205, v[82:83], s[12:13] offset:32
	v_cvt_pk_bf16_f32 v86, v86, v87
	v_cvt_pk_bf16_f32 v87, v88, v89
	global_store_dwordx2 v205, v[86:87], s[12:13] offset:48
	v_cvt_pk_bf16_f32 v90, v90, v91
	v_cvt_pk_bf16_f32 v91, v92, v93
	global_store_dwordx2 v205, v[90:91], s[12:13] offset:64
	v_cvt_pk_bf16_f32 v94, v94, v95
	v_cvt_pk_bf16_f32 v95, v96, v97
	global_store_dwordx2 v205, v[94:95], s[12:13] offset:80
	v_cvt_pk_bf16_f32 v98, v98, v99
	v_cvt_pk_bf16_f32 v99, v100, v101
	global_store_dwordx2 v205, v[98:99], s[12:13] offset:96
	v_cvt_pk_bf16_f32 v102, v102, v103
	v_cvt_pk_bf16_f32 v103, v104, v105
	global_store_dwordx2 v205, v[102:103], s[12:13] offset:112
	v_mov_b32_e32 v184, v202
	s_nop 1
	v_permlane32_swap_b32_e32 v184, v202
	v_add_f32_e32 v202, v202, v184
	v_rcp_f32_e32 v186, v202
	s_nop 0
	v_fma_f32 v184, -v202, v186, 1.0
	v_fma_f32 v186, v186, v184, v186
	v_pk_mul_f32 v[106:107], v[106:107], v[186:187] op_sel_hi:[1,0]
	v_pk_mul_f32 v[108:109], v[108:109], v[186:187] op_sel_hi:[1,0]
	v_pk_mul_f32 v[110:111], v[110:111], v[186:187] op_sel_hi:[1,0]
	v_pk_mul_f32 v[112:113], v[112:113], v[186:187] op_sel_hi:[1,0]
	v_pk_mul_f32 v[114:115], v[114:115], v[186:187] op_sel_hi:[1,0]
	v_pk_mul_f32 v[116:117], v[116:117], v[186:187] op_sel_hi:[1,0]
	v_pk_mul_f32 v[118:119], v[118:119], v[186:187] op_sel_hi:[1,0]
	v_pk_mul_f32 v[120:121], v[120:121], v[186:187] op_sel_hi:[1,0]
	v_pk_mul_f32 v[122:123], v[122:123], v[186:187] op_sel_hi:[1,0]
	v_pk_mul_f32 v[124:125], v[124:125], v[186:187] op_sel_hi:[1,0]
	v_pk_mul_f32 v[126:127], v[126:127], v[186:187] op_sel_hi:[1,0]
	v_pk_mul_f32 v[128:129], v[128:129], v[186:187] op_sel_hi:[1,0]
	v_pk_mul_f32 v[130:131], v[130:131], v[186:187] op_sel_hi:[1,0]
	v_pk_mul_f32 v[132:133], v[132:133], v[186:187] op_sel_hi:[1,0]
	v_pk_mul_f32 v[134:135], v[134:135], v[186:187] op_sel_hi:[1,0]
	v_pk_mul_f32 v[136:137], v[136:137], v[186:187] op_sel_hi:[1,0]
	v_cvt_pk_bf16_f32 v106, v106, v107
	v_cvt_pk_bf16_f32 v107, v108, v109
	global_store_dwordx2 v206, v[106:107], s[12:13]
	v_cvt_pk_bf16_f32 v110, v110, v111
	v_cvt_pk_bf16_f32 v111, v112, v113
	global_store_dwordx2 v206, v[110:111], s[12:13] offset:16
	v_cvt_pk_bf16_f32 v114, v114, v115
	v_cvt_pk_bf16_f32 v115, v116, v117
	global_store_dwordx2 v206, v[114:115], s[12:13] offset:32
	v_cvt_pk_bf16_f32 v118, v118, v119
	v_cvt_pk_bf16_f32 v119, v120, v121
	global_store_dwordx2 v206, v[118:119], s[12:13] offset:48
	v_cvt_pk_bf16_f32 v122, v122, v123
	v_cvt_pk_bf16_f32 v123, v124, v125
	global_store_dwordx2 v206, v[122:123], s[12:13] offset:64
	v_cvt_pk_bf16_f32 v126, v126, v127
	v_cvt_pk_bf16_f32 v127, v128, v129
	global_store_dwordx2 v206, v[126:127], s[12:13] offset:80
	v_cvt_pk_bf16_f32 v130, v130, v131
	v_cvt_pk_bf16_f32 v131, v132, v133
	global_store_dwordx2 v206, v[130:131], s[12:13] offset:96
	v_cvt_pk_bf16_f32 v134, v134, v135
	v_cvt_pk_bf16_f32 v135, v136, v137
	global_store_dwordx2 v206, v[134:135], s[12:13] offset:112
	s_waitcnt vmcnt(0)
	s_add_i32 s22, s22, s68
	s_cmpk_lt_i32 s22, 0x800
	s_cbranch_scc1 .Lfox_outer
	v_lshlrev_b32_e32 v2, 2, v220
	v_add_u32_e32 v3, 0x10000, v2
	ds_read_b32 v146, v2 offset:0
	ds_read_b32 v147, v2 offset:2048
	ds_read_b32 v148, v2 offset:4096
	ds_read_b32 v149, v2 offset:6144
	ds_read_b32 v150, v2 offset:8192
	ds_read_b32 v151, v2 offset:10240
	ds_read_b32 v152, v2 offset:12288
	ds_read_b32 v153, v2 offset:14336
	ds_read_b32 v154, v2 offset:16384
	ds_read_b32 v155, v2 offset:18432
	ds_read_b32 v156, v2 offset:20480
	ds_read_b32 v157, v2 offset:22528
	ds_read_b32 v158, v2 offset:24576
	ds_read_b32 v159, v2 offset:26624
	ds_read_b32 v160, v2 offset:28672
	ds_read_b32 v161, v2 offset:30720
	ds_read_b32 v162, v2 offset:32768
	ds_read_b32 v163, v2 offset:34816
	ds_read_b32 v164, v2 offset:36864
	ds_read_b32 v165, v2 offset:38912
	ds_read_b32 v166, v2 offset:40960
	ds_read_b32 v167, v2 offset:43008
	ds_read_b32 v168, v2 offset:45056
	ds_read_b32 v169, v2 offset:47104
	ds_read_b32 v170, v2 offset:49152
	ds_read_b32 v183, v2 offset:51200
	ds_read_b32 v184, v2 offset:53248
	ds_read_b32 v185, v2 offset:55296
	ds_read_b32 v186, v2 offset:57344
	ds_read_b32 v187, v2 offset:59392
	ds_read_b32 v188, v2 offset:61440
	ds_read_b32 v189, v2 offset:63488
	ds_read_b32 v190, v3 offset:0
	ds_read_b32 v191, v3 offset:2048
	ds_read_b32 v192, v3 offset:4096
	ds_read_b32 v193, v3 offset:6144
	ds_read_b32 v194, v3 offset:8192
	ds_read_b32 v195, v3 offset:10240
	ds_read_b32 v196, v3 offset:12288
	ds_read_b32 v197, v3 offset:14336
	ds_read_b32 v198, v3 offset:16384
	ds_read_b32 v199, v3 offset:18432
	ds_read_b32 v200, v3 offset:20480
	ds_read_b32 v201, v3 offset:22528
	ds_read_b32 v202, v3 offset:24576
	ds_read_b32 v203, v3 offset:26624
	ds_read_b32 v204, v3 offset:28672
	ds_read_b32 v205, v3 offset:30720
	ds_read_b32 v206, v3 offset:32768
	ds_read_b32 v207, v3 offset:34816
	ds_read_b32 v208, v3 offset:36864
	ds_read_b32 v209, v3 offset:38912
	ds_read_b32 v210, v3 offset:40960
	ds_read_b32 v211, v3 offset:43008
	ds_read_b32 v212, v3 offset:45056
	ds_read_b32 v213, v3 offset:47104
	ds_read_b32 v214, v3 offset:49152
	ds_read_b32 v215, v3 offset:51200
	ds_read_b32 v216, v3 offset:53248
	v_lshrrev_b32_e32 v2, 6, v220
	v_lshlrev_b32_e32 v2, 8, v2
	v_add_u32_e32 v2, 0x1d800, v2
	ds_read_b32 v4, v2 offset:0
	ds_read_b32 v5, v2 offset:4
	ds_read_b32 v6, v2 offset:8
	ds_read_b32 v7, v2 offset:12
	ds_read_b32 v8, v2 offset:16
	ds_read_b32 v9, v2 offset:20
	ds_read_b32 v10, v2 offset:24
	ds_read_b32 v11, v2 offset:28
	ds_read_b32 v12, v2 offset:32
	ds_read_b32 v13, v2 offset:36
	ds_read_b32 v14, v2 offset:40
	ds_read_b32 v15, v2 offset:44
	ds_read_b32 v16, v2 offset:48
	ds_read_b32 v17, v2 offset:52
	ds_read_b32 v18, v2 offset:56
	ds_read_b32 v19, v2 offset:60
	ds_read_b32 v20, v2 offset:64
	ds_read_b32 v21, v2 offset:68
	ds_read_b32 v22, v2 offset:72
	ds_read_b32 v23, v2 offset:76
	ds_read_b32 v24, v2 offset:80
	ds_read_b32 v25, v2 offset:84
	ds_read_b32 v26, v2 offset:88
	ds_read_b32 v27, v2 offset:92
	ds_read_b32 v28, v2 offset:96
	ds_read_b32 v29, v2 offset:100
	ds_read_b32 v30, v2 offset:104
	ds_read_b32 v31, v2 offset:108
	ds_read_b32 v32, v2 offset:112
	ds_read_b32 v33, v2 offset:116
	ds_read_b32 v34, v2 offset:120
	ds_read_b32 v35, v2 offset:124
	ds_read_b32 v36, v2 offset:128
	ds_read_b32 v37, v2 offset:132
	ds_read_b32 v38, v2 offset:136
	ds_read_b32 v39, v2 offset:140
	ds_read_b32 v40, v2 offset:144
	ds_read_b32 v41, v2 offset:148
	ds_read_b32 v42, v2 offset:152
	ds_read_b32 v43, v2 offset:156
	ds_read_b32 v44, v2 offset:160
	ds_read_b32 v45, v2 offset:164
	s_waitcnt lgkmcnt(0)
	v_readfirstlane_b32 s2, v4
	v_readfirstlane_b32 s3, v5
	v_readfirstlane_b32 s4, v6
	v_readfirstlane_b32 s5, v7
	v_readfirstlane_b32 s6, v8
	v_readfirstlane_b32 s7, v9
	v_readfirstlane_b32 s8, v10
	v_readfirstlane_b32 s9, v11
	v_readfirstlane_b32 s10, v12
	v_readfirstlane_b32 s11, v13
	v_readfirstlane_b32 s12, v14
	v_readfirstlane_b32 s13, v15
	v_readfirstlane_b32 s14, v16
	v_readfirstlane_b32 s15, v17
	v_readfirstlane_b32 s16, v18
	v_readfirstlane_b32 s17, v19
	v_readfirstlane_b32 s18, v20
	v_readfirstlane_b32 s19, v21
	v_readfirstlane_b32 s20, v22
	v_readfirstlane_b32 s21, v23
	v_readfirstlane_b32 s22, v24
	v_readfirstlane_b32 s23, v25
	v_readfirstlane_b32 s24, v26
	v_readfirstlane_b32 s25, v27
	v_readfirstlane_b32 s26, v28
	v_readfirstlane_b32 s27, v29
	v_readfirstlane_b32 s28, v30
	v_readfirstlane_b32 s29, v31
	v_readfirstlane_b32 s30, v32
	v_readfirstlane_b32 s31, v33
	v_readfirstlane_b32 s34, v34
	v_readfirstlane_b32 s35, v35
	v_readfirstlane_b32 s36, v36
	v_readfirstlane_b32 s37, v37
	v_readfirstlane_b32 s38, v38
	v_readfirstlane_b32 s39, v39
	v_readfirstlane_b32 s40, v40
	v_readfirstlane_b32 s41, v41
	v_readfirstlane_b32 s42, v42
	v_readfirstlane_b32 s43, v43
	v_readfirstlane_b32 s44, v44
	v_readfirstlane_b32 s45, v45
